# conv rows: second block's loads issued before the first block's reduction and stores (overlapped)
# baseline (speedup 1.0000x reference)
; template <int NR>
; __device__ __forceinline__ void conv_rows(const Args& a, int r0, int rstride, int lane) {
;     ...
;     for (int i = 0; i < NR; ++i) { const int row = r0 + i * rstride, t = row & (SEQ - 1);
;         bq[i] = *(const v4u*)(BCp + (size_t)row * 512 + c0); u0[i] = *(const v4u*)(CUp + (size_t)row * 512 + c0);
;         u1[i] = (v4u){0, 0, 0, 0}; u2[i] = (v4u){0, 0, 0, 0};
;         if (t >= 1) u1[i] = *(const v4u*)(CUp + (size_t)(row - 1) * 512 + c0);
;         if (t >= 2) u2[i] = *(const v4u*)(CUp + (size_t)(row - 2) * 512 + c0); }
;     const float* cw = a.in[I_CONVW] + c0; const float* gn = a.in[I_CONVN] + c0;
;     const f32x4 w0a = *(const f32x4*)(cw), w0b = *(const f32x4*)(cw + 4), w1a = *(const f32x4*)(cw + 512), w1b = *(const f32x4*)(cw + 516), w2a = *(const f32x4*)(cw + 1024), w2b = *(const f32x4*)(cw + 1028);
;     const f32x4 ga = *(const f32x4*)(gn), gb = *(const f32x4*)(gn + 4);
; #pragma unroll
;     for (int i = 0; i < NR; ++i) { const int row = r0 + i * rstride; float y[8]; float s = 0.f;
; #pragma unroll
;         for (int j = 0; j < 8; ++j) { const int sh = (j & 1) * 16; const unsigned ub = bq[i][j >> 1], x0 = u0[i][j >> 1], x1 = u1[i][j >> 1], x2 = u2[i][j >> 1];
;             const float B = __uint_as_float(((ub >> sh) & 0xffffu) << 16), c_0 = __uint_as_float(((x0 >> sh) & 0xffffu) << 16), c_1 = __uint_as_float(((x1 >> sh) & 0xffffu) << 16), c_2 = __uint_as_float(((x2 >> sh) & 0xffffu) << 16);
;             const float k0 = j < 4 ? w0a[j & 3] : w0b[j & 3], k1 = j < 4 ? w1a[j & 3] : w1b[j & 3], k2 = j < 4 ? w2a[j & 3] : w2b[j & 3];
;             y[j] = B * (k0 * c_2 + k1 * c_1 + k2 * c_0); s += y[j] * y[j]; }
;         s = wave_sum(s); const float rs = rsqrtf(s * (1.f / 512.f) + EPS);
.Lc5_k2_0:
	v_lshlrev_b32_e32 v184, 16, v52
	v_and_b32_e32 v185, 0xffff0000, v52
	v_lshlrev_b32_e32 v186, 16, v48
	v_and_b32_e32 v187, 0xffff0000, v48
	v_lshlrev_b32_e32 v188, 16, v44
	v_and_b32_e32 v189, 0xffff0000, v44
	v_lshlrev_b32_e32 v190, 16, v40
	v_and_b32_e32 v191, 0xffff0000, v40
	v_pk_mul_f32 v[192:193], v[2:3], v[184:185]
	v_pk_fma_f32 v[192:193], v[10:11], v[186:187], v[192:193]
	v_pk_fma_f32 v[192:193], v[18:19], v[188:189], v[192:193]
	v_pk_mul_f32 v[136:137], v[192:193], v[190:191]
	v_pk_mul_f32 v[194:195], v[136:137], v[136:137]
	v_lshlrev_b32_e32 v184, 16, v53
	v_and_b32_e32 v185, 0xffff0000, v53
	v_lshlrev_b32_e32 v186, 16, v49
	v_and_b32_e32 v187, 0xffff0000, v49
	v_lshlrev_b32_e32 v188, 16, v45
	v_and_b32_e32 v189, 0xffff0000, v45
	v_lshlrev_b32_e32 v190, 16, v41
	v_and_b32_e32 v191, 0xffff0000, v41
	v_pk_mul_f32 v[192:193], v[4:5], v[184:185]
	v_pk_fma_f32 v[192:193], v[12:13], v[186:187], v[192:193]
	v_pk_fma_f32 v[192:193], v[20:21], v[188:189], v[192:193]
	v_pk_mul_f32 v[138:139], v[192:193], v[190:191]
	v_pk_fma_f32 v[194:195], v[138:139], v[138:139], v[194:195]
	v_lshlrev_b32_e32 v184, 16, v54
	v_and_b32_e32 v185, 0xffff0000, v54
	v_lshlrev_b32_e32 v186, 16, v50
	v_and_b32_e32 v187, 0xffff0000, v50
	v_lshlrev_b32_e32 v188, 16, v46
	v_and_b32_e32 v189, 0xffff0000, v46
	v_lshlrev_b32_e32 v190, 16, v42
	v_and_b32_e32 v191, 0xffff0000, v42
	v_pk_mul_f32 v[192:193], v[6:7], v[184:185]
	v_pk_fma_f32 v[192:193], v[14:15], v[186:187], v[192:193]
	v_pk_fma_f32 v[192:193], v[22:23], v[188:189], v[192:193]
	v_pk_mul_f32 v[140:141], v[192:193], v[190:191]
	v_pk_fma_f32 v[194:195], v[140:141], v[140:141], v[194:195]
	v_lshlrev_b32_e32 v184, 16, v55
	v_and_b32_e32 v185, 0xffff0000, v55
	v_lshlrev_b32_e32 v186, 16, v51
	v_and_b32_e32 v187, 0xffff0000, v51
	v_lshlrev_b32_e32 v188, 16, v47
	v_and_b32_e32 v189, 0xffff0000, v47
	v_lshlrev_b32_e32 v190, 16, v43
	v_and_b32_e32 v191, 0xffff0000, v43
	v_pk_mul_f32 v[192:193], v[8:9], v[184:185]
	v_pk_fma_f32 v[192:193], v[16:17], v[186:187], v[192:193]
	v_pk_fma_f32 v[192:193], v[24:25], v[188:189], v[192:193]
	v_pk_mul_f32 v[142:143], v[192:193], v[190:191]
	v_pk_fma_f32 v[194:195], v[142:143], v[142:143], v[194:195]
	v_add_f32_e32 v196, v194, v195
	s_waitcnt vmcnt(16)
	s_add_i32 s10, s24, 0x600
	s_and_b32 s11, s10, 0xfff
	s_cmp_lg_u32 s11, 0
	s_cbranch_scc1 .Lc5_k1_1
	v_mov_b32_e32 v64, 0
	v_mov_b32_e32 v65, 0
	v_mov_b32_e32 v66, 0
	v_mov_b32_e32 v67, 0

; template <int NR>
; __device__ __forceinline__ void conv_rows(const Args& a, int r0, int rstride, int lane) {
;     ...
;     for (int i = 0; i < NR; ++i) { const int row = r0 + i * rstride; float y[8]; float s = 0.f;
; #pragma unroll
;         for (int j = 0; j < 8; ++j) { const int sh = (j & 1) * 16; const unsigned ub = bq[i][j >> 1], x0 = u0[i][j >> 1], x1 = u1[i][j >> 1], x2 = u2[i][j >> 1];
;             const float B = __uint_as_float(((ub >> sh) & 0xffffu) << 16), c_0 = __uint_as_float(((x0 >> sh) & 0xffffu) << 16), c_1 = __uint_as_float(((x1 >> sh) & 0xffffu) << 16), c_2 = __uint_as_float(((x2 >> sh) & 0xffffu) << 16);
;             const float k0 = j < 4 ? w0a[j & 3] : w0b[j & 3], k1 = j < 4 ? w1a[j & 3] : w1b[j & 3], k2 = j < 4 ? w2a[j & 3] : w2b[j & 3];
;             y[j] = B * (k0 * c_2 + k1 * c_1 + k2 * c_0); s += y[j] * y[j]; }
;         s = wave_sum(s); const float rs = rsqrtf(s * (1.f / 512.f) + EPS);
.Lc5_k2_1:
	v_lshlrev_b32_e32 v184, 16, v68
	v_and_b32_e32 v185, 0xffff0000, v68
	v_lshlrev_b32_e32 v186, 16, v64
	v_and_b32_e32 v187, 0xffff0000, v64
	v_lshlrev_b32_e32 v188, 16, v60
	v_and_b32_e32 v189, 0xffff0000, v60
	v_lshlrev_b32_e32 v190, 16, v56
	v_and_b32_e32 v191, 0xffff0000, v56
	v_pk_mul_f32 v[192:193], v[2:3], v[184:185]
	v_pk_fma_f32 v[192:193], v[10:11], v[186:187], v[192:193]
	v_pk_fma_f32 v[192:193], v[18:19], v[188:189], v[192:193]
	v_pk_mul_f32 v[144:145], v[192:193], v[190:191]
	v_pk_mul_f32 v[194:195], v[144:145], v[144:145]
	v_lshlrev_b32_e32 v184, 16, v69
	v_and_b32_e32 v185, 0xffff0000, v69
	v_lshlrev_b32_e32 v186, 16, v65
	v_and_b32_e32 v187, 0xffff0000, v65
	v_lshlrev_b32_e32 v188, 16, v61
	v_and_b32_e32 v189, 0xffff0000, v61
	v_lshlrev_b32_e32 v190, 16, v57
	v_and_b32_e32 v191, 0xffff0000, v57
	v_pk_mul_f32 v[192:193], v[4:5], v[184:185]
	v_pk_fma_f32 v[192:193], v[12:13], v[186:187], v[192:193]
	v_pk_fma_f32 v[192:193], v[20:21], v[188:189], v[192:193]
	v_pk_mul_f32 v[146:147], v[192:193], v[190:191]
	v_pk_fma_f32 v[194:195], v[146:147], v[146:147], v[194:195]
	v_lshlrev_b32_e32 v184, 16, v70
	v_and_b32_e32 v185, 0xffff0000, v70
	v_lshlrev_b32_e32 v186, 16, v66
	v_and_b32_e32 v187, 0xffff0000, v66
	v_lshlrev_b32_e32 v188, 16, v62
	v_and_b32_e32 v189, 0xffff0000, v62
	v_lshlrev_b32_e32 v190, 16, v58
	v_and_b32_e32 v191, 0xffff0000, v58
	v_pk_mul_f32 v[192:193], v[6:7], v[184:185]
	v_pk_fma_f32 v[192:193], v[14:15], v[186:187], v[192:193]
	v_pk_fma_f32 v[192:193], v[22:23], v[188:189], v[192:193]
	v_pk_mul_f32 v[148:149], v[192:193], v[190:191]
	v_pk_fma_f32 v[194:195], v[148:149], v[148:149], v[194:195]
	v_lshlrev_b32_e32 v184, 16, v71
	v_and_b32_e32 v185, 0xffff0000, v71
	v_lshlrev_b32_e32 v186, 16, v67
	v_and_b32_e32 v187, 0xffff0000, v67
	v_lshlrev_b32_e32 v188, 16, v63
	v_and_b32_e32 v189, 0xffff0000, v63
	v_lshlrev_b32_e32 v190, 16, v59
	v_and_b32_e32 v191, 0xffff0000, v59
	v_pk_mul_f32 v[192:193], v[8:9], v[184:185]
	v_pk_fma_f32 v[192:193], v[16:17], v[186:187], v[192:193]
	v_pk_fma_f32 v[192:193], v[24:25], v[188:189], v[192:193]
	v_pk_mul_f32 v[150:151], v[192:193], v[190:191]
	v_pk_fma_f32 v[194:195], v[150:151], v[150:151], v[194:195]
	v_add_f32_e32 v198, v194, v195
	s_waitcnt vmcnt(12)
	s_add_i32 s10, s24, 0xc00
	s_and_b32 s11, s10, 0xfff
	s_cmp_lg_u32 s11, 0
	s_cbranch_scc1 .Lc5_k1_2
	v_mov_b32_e32 v80, 0
	v_mov_b32_e32 v81, 0
	v_mov_b32_e32 v82, 0
	v_mov_b32_e32 v83, 0

; template <int NR>
; __device__ __forceinline__ void conv_rows(const Args& a, int r0, int rstride, int lane) {
;     ...
;     for (int i = 0; i < NR; ++i) { const int row = r0 + i * rstride; float y[8]; float s = 0.f;
; #pragma unroll
;         for (int j = 0; j < 8; ++j) { const int sh = (j & 1) * 16; const unsigned ub = bq[i][j >> 1], x0 = u0[i][j >> 1], x1 = u1[i][j >> 1], x2 = u2[i][j >> 1];
;             const float B = __uint_as_float(((ub >> sh) & 0xffffu) << 16), c_0 = __uint_as_float(((x0 >> sh) & 0xffffu) << 16), c_1 = __uint_as_float(((x1 >> sh) & 0xffffu) << 16), c_2 = __uint_as_float(((x2 >> sh) & 0xffffu) << 16);
;             const float k0 = j < 4 ? w0a[j & 3] : w0b[j & 3], k1 = j < 4 ? w1a[j & 3] : w1b[j & 3], k2 = j < 4 ? w2a[j & 3] : w2b[j & 3];
;             y[j] = B * (k0 * c_2 + k1 * c_1 + k2 * c_0); s += y[j] * y[j]; }
;         s = wave_sum(s); const float rs = rsqrtf(s * (1.f / 512.f) + EPS);
.Lc5_k2_2:
	v_lshlrev_b32_e32 v184, 16, v84
	v_and_b32_e32 v185, 0xffff0000, v84
	v_lshlrev_b32_e32 v186, 16, v80
	v_and_b32_e32 v187, 0xffff0000, v80
	v_lshlrev_b32_e32 v188, 16, v76
	v_and_b32_e32 v189, 0xffff0000, v76
	v_lshlrev_b32_e32 v190, 16, v72
	v_and_b32_e32 v191, 0xffff0000, v72
	v_pk_mul_f32 v[192:193], v[2:3], v[184:185]
	v_pk_fma_f32 v[192:193], v[10:11], v[186:187], v[192:193]
	v_pk_fma_f32 v[192:193], v[18:19], v[188:189], v[192:193]
	v_pk_mul_f32 v[152:153], v[192:193], v[190:191]
	v_pk_mul_f32 v[194:195], v[152:153], v[152:153]
	v_lshlrev_b32_e32 v184, 16, v85
	v_and_b32_e32 v185, 0xffff0000, v85
	v_lshlrev_b32_e32 v186, 16, v81
	v_and_b32_e32 v187, 0xffff0000, v81
	v_lshlrev_b32_e32 v188, 16, v77
	v_and_b32_e32 v189, 0xffff0000, v77
	v_lshlrev_b32_e32 v190, 16, v73
	v_and_b32_e32 v191, 0xffff0000, v73
	v_pk_mul_f32 v[192:193], v[4:5], v[184:185]
	v_pk_fma_f32 v[192:193], v[12:13], v[186:187], v[192:193]
	v_pk_fma_f32 v[192:193], v[20:21], v[188:189], v[192:193]
	v_pk_mul_f32 v[154:155], v[192:193], v[190:191]
	v_pk_fma_f32 v[194:195], v[154:155], v[154:155], v[194:195]
	v_lshlrev_b32_e32 v184, 16, v86
	v_and_b32_e32 v185, 0xffff0000, v86
	v_lshlrev_b32_e32 v186, 16, v82
	v_and_b32_e32 v187, 0xffff0000, v82
	v_lshlrev_b32_e32 v188, 16, v78
	v_and_b32_e32 v189, 0xffff0000, v78
	v_lshlrev_b32_e32 v190, 16, v74
	v_and_b32_e32 v191, 0xffff0000, v74
	v_pk_mul_f32 v[192:193], v[6:7], v[184:185]
	v_pk_fma_f32 v[192:193], v[14:15], v[186:187], v[192:193]
	v_pk_fma_f32 v[192:193], v[22:23], v[188:189], v[192:193]
	v_pk_mul_f32 v[156:157], v[192:193], v[190:191]
	v_pk_fma_f32 v[194:195], v[156:157], v[156:157], v[194:195]
	v_lshlrev_b32_e32 v184, 16, v87
	v_and_b32_e32 v185, 0xffff0000, v87
	v_lshlrev_b32_e32 v186, 16, v83
	v_and_b32_e32 v187, 0xffff0000, v83
	v_lshlrev_b32_e32 v188, 16, v79
	v_and_b32_e32 v189, 0xffff0000, v79
	v_lshlrev_b32_e32 v190, 16, v75
	v_and_b32_e32 v191, 0xffff0000, v75
	v_pk_mul_f32 v[192:193], v[8:9], v[184:185]
	v_pk_fma_f32 v[192:193], v[16:17], v[186:187], v[192:193]
	v_pk_fma_f32 v[192:193], v[24:25], v[188:189], v[192:193]
	v_pk_mul_f32 v[158:159], v[192:193], v[190:191]
	v_pk_fma_f32 v[194:195], v[158:159], v[158:159], v[194:195]
	v_add_f32_e32 v200, v194, v195
	s_waitcnt vmcnt(8)
	s_add_i32 s10, s24, 0x1200
	s_and_b32 s11, s10, 0xfff
	s_cmp_lg_u32 s11, 0
	s_cbranch_scc1 .Lc5_k1_3
	v_mov_b32_e32 v96, 0
	v_mov_b32_e32 v97, 0
	v_mov_b32_e32 v98, 0
	v_mov_b32_e32 v99, 0

; template <int NR>
; __device__ __forceinline__ void conv_rows(const Args& a, int r0, int rstride, int lane) {
;     ...
;     for (int i = 0; i < NR; ++i) { const int row = r0 + i * rstride; float y[8]; float s = 0.f;
; #pragma unroll
;         for (int j = 0; j < 8; ++j) { const int sh = (j & 1) * 16; const unsigned ub = bq[i][j >> 1], x0 = u0[i][j >> 1], x1 = u1[i][j >> 1], x2 = u2[i][j >> 1];
;             const float B = __uint_as_float(((ub >> sh) & 0xffffu) << 16), c_0 = __uint_as_float(((x0 >> sh) & 0xffffu) << 16), c_1 = __uint_as_float(((x1 >> sh) & 0xffffu) << 16), c_2 = __uint_as_float(((x2 >> sh) & 0xffffu) << 16);
;             const float k0 = j < 4 ? w0a[j & 3] : w0b[j & 3], k1 = j < 4 ? w1a[j & 3] : w1b[j & 3], k2 = j < 4 ? w2a[j & 3] : w2b[j & 3];
;             y[j] = B * (k0 * c_2 + k1 * c_1 + k2 * c_0); s += y[j] * y[j]; }
;         s = wave_sum(s); const float rs = rsqrtf(s * (1.f / 512.f) + EPS);
.Lc5_k2_3:
	v_lshlrev_b32_e32 v184, 16, v100
	v_and_b32_e32 v185, 0xffff0000, v100
	v_lshlrev_b32_e32 v186, 16, v96
	v_and_b32_e32 v187, 0xffff0000, v96
	v_lshlrev_b32_e32 v188, 16, v92
	v_and_b32_e32 v189, 0xffff0000, v92
	v_lshlrev_b32_e32 v190, 16, v88
	v_and_b32_e32 v191, 0xffff0000, v88
	v_pk_mul_f32 v[192:193], v[2:3], v[184:185]
	v_pk_fma_f32 v[192:193], v[10:11], v[186:187], v[192:193]
	v_pk_fma_f32 v[192:193], v[18:19], v[188:189], v[192:193]
	v_pk_mul_f32 v[160:161], v[192:193], v[190:191]
	v_pk_mul_f32 v[194:195], v[160:161], v[160:161]
	v_lshlrev_b32_e32 v184, 16, v101
	v_and_b32_e32 v185, 0xffff0000, v101
	v_lshlrev_b32_e32 v186, 16, v97
	v_and_b32_e32 v187, 0xffff0000, v97
	v_lshlrev_b32_e32 v188, 16, v93
	v_and_b32_e32 v189, 0xffff0000, v93
	v_lshlrev_b32_e32 v190, 16, v89
	v_and_b32_e32 v191, 0xffff0000, v89
	v_pk_mul_f32 v[192:193], v[4:5], v[184:185]
	v_pk_fma_f32 v[192:193], v[12:13], v[186:187], v[192:193]
	v_pk_fma_f32 v[192:193], v[20:21], v[188:189], v[192:193]
	v_pk_mul_f32 v[162:163], v[192:193], v[190:191]
	v_pk_fma_f32 v[194:195], v[162:163], v[162:163], v[194:195]
	v_lshlrev_b32_e32 v184, 16, v102
	v_and_b32_e32 v185, 0xffff0000, v102
	v_lshlrev_b32_e32 v186, 16, v98
	v_and_b32_e32 v187, 0xffff0000, v98
	v_lshlrev_b32_e32 v188, 16, v94
	v_and_b32_e32 v189, 0xffff0000, v94
	v_lshlrev_b32_e32 v190, 16, v90
	v_and_b32_e32 v191, 0xffff0000, v90
	v_pk_mul_f32 v[192:193], v[6:7], v[184:185]
	v_pk_fma_f32 v[192:193], v[14:15], v[186:187], v[192:193]
	v_pk_fma_f32 v[192:193], v[22:23], v[188:189], v[192:193]
	v_pk_mul_f32 v[164:165], v[192:193], v[190:191]
	v_pk_fma_f32 v[194:195], v[164:165], v[164:165], v[194:195]
	v_lshlrev_b32_e32 v184, 16, v103
	v_and_b32_e32 v185, 0xffff0000, v103
	v_lshlrev_b32_e32 v186, 16, v99
	v_and_b32_e32 v187, 0xffff0000, v99
	v_lshlrev_b32_e32 v188, 16, v95
	v_and_b32_e32 v189, 0xffff0000, v95
	v_lshlrev_b32_e32 v190, 16, v91
	v_and_b32_e32 v191, 0xffff0000, v91
	v_pk_mul_f32 v[192:193], v[8:9], v[184:185]
	v_pk_fma_f32 v[192:193], v[16:17], v[186:187], v[192:193]
	v_pk_fma_f32 v[192:193], v[24:25], v[188:189], v[192:193]
	v_pk_mul_f32 v[166:167], v[192:193], v[190:191]
	v_pk_fma_f32 v[194:195], v[166:167], v[166:167], v[194:195]
	v_add_f32_e32 v202, v194, v195
	s_waitcnt vmcnt(4)
	s_add_i32 s10, s24, 0x1800
	s_and_b32 s11, s10, 0xfff
	s_cmp_lg_u32 s11, 0
	s_cbranch_scc1 .Lc5_k1_4
	v_mov_b32_e32 v112, 0
	v_mov_b32_e32 v113, 0
	v_mov_b32_e32 v114, 0
	v_mov_b32_e32 v115, 0

; template <int NR>
; __device__ __forceinline__ void conv_rows(const Args& a, int r0, int rstride, int lane) {
;     ...
;     for (int i = 0; i < NR; ++i) { const int row = r0 + i * rstride; float y[8]; float s = 0.f;
; #pragma unroll
;         for (int j = 0; j < 8; ++j) { const int sh = (j & 1) * 16; const unsigned ub = bq[i][j >> 1], x0 = u0[i][j >> 1], x1 = u1[i][j >> 1], x2 = u2[i][j >> 1];
;             const float B = __uint_as_float(((ub >> sh) & 0xffffu) << 16), c_0 = __uint_as_float(((x0 >> sh) & 0xffffu) << 16), c_1 = __uint_as_float(((x1 >> sh) & 0xffffu) << 16), c_2 = __uint_as_float(((x2 >> sh) & 0xffffu) << 16);
;             const float k0 = j < 4 ? w0a[j & 3] : w0b[j & 3], k1 = j < 4 ? w1a[j & 3] : w1b[j & 3], k2 = j < 4 ? w2a[j & 3] : w2b[j & 3];
;             y[j] = B * (k0 * c_2 + k1 * c_1 + k2 * c_0); s += y[j] * y[j]; }
;         s = wave_sum(s); const float rs = rsqrtf(s * (1.f / 512.f) + EPS);
.Lc5_k2_4:
	v_lshlrev_b32_e32 v184, 16, v116
	v_and_b32_e32 v185, 0xffff0000, v116
	v_lshlrev_b32_e32 v186, 16, v112
	v_and_b32_e32 v187, 0xffff0000, v112
	v_lshlrev_b32_e32 v188, 16, v108
	v_and_b32_e32 v189, 0xffff0000, v108
	v_lshlrev_b32_e32 v190, 16, v104
	v_and_b32_e32 v191, 0xffff0000, v104
	v_pk_mul_f32 v[192:193], v[2:3], v[184:185]
	v_pk_fma_f32 v[192:193], v[10:11], v[186:187], v[192:193]
	v_pk_fma_f32 v[192:193], v[18:19], v[188:189], v[192:193]
	v_pk_mul_f32 v[168:169], v[192:193], v[190:191]
	v_pk_mul_f32 v[194:195], v[168:169], v[168:169]
	v_lshlrev_b32_e32 v184, 16, v117
	v_and_b32_e32 v185, 0xffff0000, v117
	v_lshlrev_b32_e32 v186, 16, v113
	v_and_b32_e32 v187, 0xffff0000, v113
	v_lshlrev_b32_e32 v188, 16, v109
	v_and_b32_e32 v189, 0xffff0000, v109
	v_lshlrev_b32_e32 v190, 16, v105
	v_and_b32_e32 v191, 0xffff0000, v105
	v_pk_mul_f32 v[192:193], v[4:5], v[184:185]
	v_pk_fma_f32 v[192:193], v[12:13], v[186:187], v[192:193]
	v_pk_fma_f32 v[192:193], v[20:21], v[188:189], v[192:193]
	v_pk_mul_f32 v[170:171], v[192:193], v[190:191]
	v_pk_fma_f32 v[194:195], v[170:171], v[170:171], v[194:195]
	v_lshlrev_b32_e32 v184, 16, v118
	v_and_b32_e32 v185, 0xffff0000, v118
	v_lshlrev_b32_e32 v186, 16, v114
	v_and_b32_e32 v187, 0xffff0000, v114
	v_lshlrev_b32_e32 v188, 16, v110
	v_and_b32_e32 v189, 0xffff0000, v110
	v_lshlrev_b32_e32 v190, 16, v106
	v_and_b32_e32 v191, 0xffff0000, v106
	v_pk_mul_f32 v[192:193], v[6:7], v[184:185]
	v_pk_fma_f32 v[192:193], v[14:15], v[186:187], v[192:193]
	v_pk_fma_f32 v[192:193], v[22:23], v[188:189], v[192:193]
	v_pk_mul_f32 v[172:173], v[192:193], v[190:191]
	v_pk_fma_f32 v[194:195], v[172:173], v[172:173], v[194:195]
	v_lshlrev_b32_e32 v184, 16, v119
	v_and_b32_e32 v185, 0xffff0000, v119
	v_lshlrev_b32_e32 v186, 16, v115
	v_and_b32_e32 v187, 0xffff0000, v115
	v_lshlrev_b32_e32 v188, 16, v111
	v_and_b32_e32 v189, 0xffff0000, v111
	v_lshlrev_b32_e32 v190, 16, v107
	v_and_b32_e32 v191, 0xffff0000, v107
	v_pk_mul_f32 v[192:193], v[8:9], v[184:185]
	v_pk_fma_f32 v[192:193], v[16:17], v[186:187], v[192:193]
	v_pk_fma_f32 v[192:193], v[24:25], v[188:189], v[192:193]
	v_pk_mul_f32 v[174:175], v[192:193], v[190:191]
	v_pk_fma_f32 v[194:195], v[174:175], v[174:175], v[194:195]
	v_add_f32_e32 v204, v194, v195
	s_waitcnt vmcnt(0)
	s_add_i32 s10, s24, 0x1e00
	s_and_b32 s11, s10, 0xfff
	s_cmp_lg_u32 s11, 0
	s_cbranch_scc1 .Lc5_k1_5
	v_mov_b32_e32 v128, 0
	v_mov_b32_e32 v129, 0
	v_mov_b32_e32 v130, 0
	v_mov_b32_e32 v131, 0

; __device__ __forceinline__ unsigned pk2(float lo, float hi) { return pg8::cvt_pk_bf16(lo, hi); }
; template <int NR>
; __device__ __forceinline__ void conv_rows(const Args& a, int r0, int rstride, int lane) {
;     ...
;     for (int i = 0; i < NR; ++i) { const int row = r0 + i * rstride, t = row & (SEQ - 1);
;         bq[i] = *(const v4u*)(BCp + (size_t)row * 512 + c0); u0[i] = *(const v4u*)(CUp + (size_t)row * 512 + c0);
;         u1[i] = (v4u){0, 0, 0, 0}; u2[i] = (v4u){0, 0, 0, 0};
;         if (t >= 1) u1[i] = *(const v4u*)(CUp + (size_t)(row - 1) * 512 + c0);
;         if (t >= 2) u2[i] = *(const v4u*)(CUp + (size_t)(row - 2) * 512 + c0); }
;     const float* cw = a.in[I_CONVW] + c0; const float* gn = a.in[I_CONVN] + c0;
;     const f32x4 w0a = *(const f32x4*)(cw), w0b = *(const f32x4*)(cw + 4), w1a = *(const f32x4*)(cw + 512), w1b = *(const f32x4*)(cw + 516), w2a = *(const f32x4*)(cw + 1024), w2b = *(const f32x4*)(cw + 1028);
;     const f32x4 ga = *(const f32x4*)(gn), gb = *(const f32x4*)(gn + 4);
; #pragma unroll
;     for (int i = 0; i < NR; ++i) { const int row = r0 + i * rstride; float y[8]; float s = 0.f;
; #pragma unroll
;         for (int j = 0; j < 8; ++j) { const int sh = (j & 1) * 16; const unsigned ub = bq[i][j >> 1], x0 = u0[i][j >> 1], x1 = u1[i][j >> 1], x2 = u2[i][j >> 1];
;             const float B = __uint_as_float(((ub >> sh) & 0xffffu) << 16), c_0 = __uint_as_float(((x0 >> sh) & 0xffffu) << 16), c_1 = __uint_as_float(((x1 >> sh) & 0xffffu) << 16), c_2 = __uint_as_float(((x2 >> sh) & 0xffffu) << 16);
;             const float k0 = j < 4 ? w0a[j & 3] : w0b[j & 3], k1 = j < 4 ? w1a[j & 3] : w1b[j & 3], k2 = j < 4 ? w2a[j & 3] : w2b[j & 3];
;             y[j] = B * (k0 * c_2 + k1 * c_1 + k2 * c_0); s += y[j] * y[j]; }
;         s = wave_sum(s); const float rs = rsqrtf(s * (1.f / 512.f) + EPS);
;         v4u o; o.x = pk2(y[0] * rs * ga[0], y[1] * rs * ga[1]); o.y = pk2(y[2] * rs * ga[2], y[3] * rs * ga[3]); o.z = pk2(y[4] * rs * gb[0], y[5] * rs * gb[1]); o.w = pk2(y[6] * rs * gb[2], y[7] * rs * gb[3]);
;         pg8::st_wt16((bf16*)(ws + WS_MIX) + (size_t)row * 1024 + 512 + c0, o); }
.Lc5_k2_5:
	v_lshlrev_b32_e32 v184, 16, v132
	v_and_b32_e32 v185, 0xffff0000, v132
	v_lshlrev_b32_e32 v186, 16, v128
	v_and_b32_e32 v187, 0xffff0000, v128
	v_lshlrev_b32_e32 v188, 16, v124
	v_and_b32_e32 v189, 0xffff0000, v124
	v_lshlrev_b32_e32 v190, 16, v120
	v_and_b32_e32 v191, 0xffff0000, v120
	v_pk_mul_f32 v[192:193], v[2:3], v[184:185]
	v_pk_fma_f32 v[192:193], v[10:11], v[186:187], v[192:193]
	v_pk_fma_f32 v[192:193], v[18:19], v[188:189], v[192:193]
	v_pk_mul_f32 v[176:177], v[192:193], v[190:191]
	v_pk_mul_f32 v[194:195], v[176:177], v[176:177]
	v_lshlrev_b32_e32 v184, 16, v133
	v_and_b32_e32 v185, 0xffff0000, v133
	v_lshlrev_b32_e32 v186, 16, v129
	v_and_b32_e32 v187, 0xffff0000, v129
	v_lshlrev_b32_e32 v188, 16, v125
	v_and_b32_e32 v189, 0xffff0000, v125
	v_lshlrev_b32_e32 v190, 16, v121
	v_and_b32_e32 v191, 0xffff0000, v121
	v_pk_mul_f32 v[192:193], v[4:5], v[184:185]
	v_pk_fma_f32 v[192:193], v[12:13], v[186:187], v[192:193]
	v_pk_fma_f32 v[192:193], v[20:21], v[188:189], v[192:193]
	v_pk_mul_f32 v[178:179], v[192:193], v[190:191]
	v_pk_fma_f32 v[194:195], v[178:179], v[178:179], v[194:195]
	v_lshlrev_b32_e32 v184, 16, v134
	v_and_b32_e32 v185, 0xffff0000, v134
	v_lshlrev_b32_e32 v186, 16, v130
	v_and_b32_e32 v187, 0xffff0000, v130
	v_lshlrev_b32_e32 v188, 16, v126
	v_and_b32_e32 v189, 0xffff0000, v126
	v_lshlrev_b32_e32 v190, 16, v122
	v_and_b32_e32 v191, 0xffff0000, v122
	v_pk_mul_f32 v[192:193], v[6:7], v[184:185]
	v_pk_fma_f32 v[192:193], v[14:15], v[186:187], v[192:193]
	v_pk_fma_f32 v[192:193], v[22:23], v[188:189], v[192:193]
	v_pk_mul_f32 v[180:181], v[192:193], v[190:191]
	v_pk_fma_f32 v[194:195], v[180:181], v[180:181], v[194:195]
	v_lshlrev_b32_e32 v184, 16, v135
	v_and_b32_e32 v185, 0xffff0000, v135
	v_lshlrev_b32_e32 v186, 16, v131
	v_and_b32_e32 v187, 0xffff0000, v131
	v_lshlrev_b32_e32 v188, 16, v127
	v_and_b32_e32 v189, 0xffff0000, v127
	v_lshlrev_b32_e32 v190, 16, v123
	v_and_b32_e32 v191, 0xffff0000, v123
	v_pk_mul_f32 v[192:193], v[8:9], v[184:185]
	v_pk_fma_f32 v[192:193], v[16:17], v[186:187], v[192:193]
	v_pk_fma_f32 v[192:193], v[24:25], v[188:189], v[192:193]
	v_pk_mul_f32 v[182:183], v[192:193], v[190:191]
	v_pk_fma_f32 v[194:195], v[182:183], v[182:183], v[194:195]
	v_add_f32_e32 v206, v194, v195
	s_add_i32 s10, s24, 0x2400
	s_lshl_b32 s11, s10, 10
	s_add_u32 s4, s20, s11
	s_addc_u32 s5, s21, 0
	s_add_u32 s6, s22, s11
	s_addc_u32 s7, s23, 0
	global_load_dwordx4 v[40:43], v0, s[4:5]
	global_load_dwordx4 v[44:47], v0, s[6:7]
	global_load_dwordx4 v[48:51], v0, s[6:7] offset:-1024
	global_load_dwordx4 v[52:55], v0, s[6:7] offset:-2048
	s_add_i32 s10, s24, 0x2a00
	s_lshl_b32 s11, s10, 10
	s_add_u32 s4, s20, s11
	s_addc_u32 s5, s21, 0
	s_add_u32 s6, s22, s11
	s_addc_u32 s7, s23, 0
	global_load_dwordx4 v[56:59], v0, s[4:5]
	global_load_dwordx4 v[60:63], v0, s[6:7]
	global_load_dwordx4 v[64:67], v0, s[6:7] offset:-1024
	global_load_dwordx4 v[68:71], v0, s[6:7] offset:-2048
	s_add_i32 s10, s24, 0x3000
	s_lshl_b32 s11, s10, 10
	s_add_u32 s4, s20, s11
	s_addc_u32 s5, s21, 0
	s_add_u32 s6, s22, s11
	s_addc_u32 s7, s23, 0
	global_load_dwordx4 v[72:75], v0, s[4:5]
	global_load_dwordx4 v[76:79], v0, s[6:7]
	global_load_dwordx4 v[80:83], v0, s[6:7] offset:-1024
	global_load_dwordx4 v[84:87], v0, s[6:7] offset:-2048
	s_add_i32 s10, s24, 0x3600
	s_lshl_b32 s11, s10, 10
	s_add_u32 s4, s20, s11
	s_addc_u32 s5, s21, 0
	s_add_u32 s6, s22, s11
	s_addc_u32 s7, s23, 0
	global_load_dwordx4 v[88:91], v0, s[4:5]
	global_load_dwordx4 v[92:95], v0, s[6:7]
	global_load_dwordx4 v[96:99], v0, s[6:7] offset:-1024
	global_load_dwordx4 v[100:103], v0, s[6:7] offset:-2048
	s_add_i32 s10, s24, 0x3c00
	s_cmpk_lt_u32 s24, 0x400
	s_cselect_b32 s10, s10, s24
	s_lshl_b32 s11, s10, 10
	s_add_u32 s4, s20, s11
	s_addc_u32 s5, s21, 0
	s_add_u32 s6, s22, s11
	s_addc_u32 s7, s23, 0
	global_load_dwordx4 v[104:107], v0, s[4:5]
	global_load_dwordx4 v[108:111], v0, s[6:7]
	global_load_dwordx4 v[112:115], v0, s[6:7] offset:-1024
	global_load_dwordx4 v[116:119], v0, s[6:7] offset:-2048
	v_xor_b32_e32 v210, 32, v208
	v_lshlrev_b32_e32 v210, 2, v210
	v_xor_b32_e32 v211, 16, v208
	v_lshlrev_b32_e32 v211, 2, v211
	v_xor_b32_e32 v212, 8, v208
	v_lshlrev_b32_e32 v212, 2, v212
	v_xor_b32_e32 v213, 4, v208
	v_lshlrev_b32_e32 v213, 2, v213
	v_xor_b32_e32 v214, 2, v208
	v_lshlrev_b32_e32 v214, 2, v214
	v_xor_b32_e32 v215, 1, v208
	v_lshlrev_b32_e32 v215, 2, v215
	v_mov_b32_e32 v216, 0x358637bd
	ds_bpermute_b32 v218, v210, v196
	ds_bpermute_b32 v220, v210, v198
	ds_bpermute_b32 v222, v210, v200
	ds_bpermute_b32 v224, v210, v202
	ds_bpermute_b32 v226, v210, v204
	ds_bpermute_b32 v228, v210, v206
	s_waitcnt lgkmcnt(0)
	v_add_f32_e32 v196, v196, v218
	v_add_f32_e32 v198, v198, v220
	v_add_f32_e32 v200, v200, v222
	v_add_f32_e32 v202, v202, v224
	v_add_f32_e32 v204, v204, v226
	v_add_f32_e32 v206, v206, v228
	ds_bpermute_b32 v218, v211, v196
	ds_bpermute_b32 v220, v211, v198
	ds_bpermute_b32 v222, v211, v200
	ds_bpermute_b32 v224, v211, v202
	ds_bpermute_b32 v226, v211, v204
	ds_bpermute_b32 v228, v211, v206
	s_waitcnt lgkmcnt(0)
	v_add_f32_e32 v196, v196, v218
	v_add_f32_e32 v198, v198, v220
	v_add_f32_e32 v200, v200, v222
	v_add_f32_e32 v202, v202, v224
	v_add_f32_e32 v204, v204, v226
	v_add_f32_e32 v206, v206, v228
	ds_bpermute_b32 v218, v212, v196
	ds_bpermute_b32 v220, v212, v198
	ds_bpermute_b32 v222, v212, v200
	ds_bpermute_b32 v224, v212, v202
	ds_bpermute_b32 v226, v212, v204
	ds_bpermute_b32 v228, v212, v206
	s_waitcnt lgkmcnt(0)
; __device__ __forceinline__ unsigned pk2(float lo, float hi) { return pg8::cvt_pk_bf16(lo, hi); }
; template <int NR>
; __device__ __forceinline__ void conv_rows(const Args& a, int r0, int rstride, int lane) {
;     ...
;     for (int i = 0; i < NR; ++i) { const int row = r0 + i * rstride; float y[8]; float s = 0.f;
; #pragma unroll
;         for (int j = 0; j < 8; ++j) { const int sh = (j & 1) * 16; const unsigned ub = bq[i][j >> 1], x0 = u0[i][j >> 1], x1 = u1[i][j >> 1], x2 = u2[i][j >> 1];
;             const float B = __uint_as_float(((ub >> sh) & 0xffffu) << 16), c_0 = __uint_as_float(((x0 >> sh) & 0xffffu) << 16), c_1 = __uint_as_float(((x1 >> sh) & 0xffffu) << 16), c_2 = __uint_as_float(((x2 >> sh) & 0xffffu) << 16);
;             const float k0 = j < 4 ? w0a[j & 3] : w0b[j & 3], k1 = j < 4 ? w1a[j & 3] : w1b[j & 3], k2 = j < 4 ? w2a[j & 3] : w2b[j & 3];
;             y[j] = B * (k0 * c_2 + k1 * c_1 + k2 * c_0); s += y[j] * y[j]; }
;         s = wave_sum(s); const float rs = rsqrtf(s * (1.f / 512.f) + EPS);
;         v4u o; o.x = pk2(y[0] * rs * ga[0], y[1] * rs * ga[1]); o.y = pk2(y[2] * rs * ga[2], y[3] * rs * ga[3]); o.z = pk2(y[4] * rs * gb[0], y[5] * rs * gb[1]); o.w = pk2(y[6] * rs * gb[2], y[7] * rs * gb[3]);
;         pg8::st_wt16((bf16*)(ws + WS_MIX) + (size_t)row * 1024 + 512 + c0, o); }
	v_add_f32_e32 v196, v196, v218
	v_add_f32_e32 v198, v198, v220
	v_add_f32_e32 v200, v200, v222
	v_add_f32_e32 v202, v202, v224
	v_add_f32_e32 v204, v204, v226
	v_add_f32_e32 v206, v206, v228
	ds_bpermute_b32 v218, v213, v196
	ds_bpermute_b32 v220, v213, v198
	ds_bpermute_b32 v222, v213, v200
	ds_bpermute_b32 v224, v213, v202
	ds_bpermute_b32 v226, v213, v204
	ds_bpermute_b32 v228, v213, v206
	s_waitcnt lgkmcnt(0)
	v_add_f32_e32 v196, v196, v218
	v_add_f32_e32 v198, v198, v220
	v_add_f32_e32 v200, v200, v222
	v_add_f32_e32 v202, v202, v224
	v_add_f32_e32 v204, v204, v226
	v_add_f32_e32 v206, v206, v228
	ds_bpermute_b32 v218, v214, v196
	ds_bpermute_b32 v220, v214, v198
	ds_bpermute_b32 v222, v214, v200
	ds_bpermute_b32 v224, v214, v202
	ds_bpermute_b32 v226, v214, v204
	ds_bpermute_b32 v228, v214, v206
	s_waitcnt lgkmcnt(0)
	v_add_f32_e32 v196, v196, v218
	v_add_f32_e32 v198, v198, v220
	v_add_f32_e32 v200, v200, v222
	v_add_f32_e32 v202, v202, v224
	v_add_f32_e32 v204, v204, v226
	v_add_f32_e32 v206, v206, v228
	ds_bpermute_b32 v218, v215, v196
	ds_bpermute_b32 v220, v215, v198
	ds_bpermute_b32 v222, v215, v200
	ds_bpermute_b32 v224, v215, v202
	ds_bpermute_b32 v226, v215, v204
	ds_bpermute_b32 v228, v215, v206
	s_waitcnt lgkmcnt(0)
	v_add_f32_e32 v196, v196, v218
	v_add_f32_e32 v198, v198, v220
	v_add_f32_e32 v200, v200, v222
	v_add_f32_e32 v202, v202, v224
	v_add_f32_e32 v204, v204, v226
	v_add_f32_e32 v206, v206, v228
	v_fmamk_f32 v196, v196, 0x3b000000, v216
	v_fmamk_f32 v198, v198, 0x3b000000, v216
	v_fmamk_f32 v200, v200, 0x3b000000, v216
	v_fmamk_f32 v202, v202, 0x3b000000, v216
	v_fmamk_f32 v204, v204, 0x3b000000, v216
	v_fmamk_f32 v206, v206, 0x3b000000, v216
	v_rsq_f32_e32 v196, v196
	v_rsq_f32_e32 v198, v198
	v_rsq_f32_e32 v200, v200
	v_rsq_f32_e32 v202, v202
	v_rsq_f32_e32 v204, v204
	v_rsq_f32_e32 v206, v206
	s_nop 1
	v_pk_mul_f32 v[184:185], v[136:137], v[196:197] op_sel_hi:[1,0]
	v_pk_mul_f32 v[186:187], v[138:139], v[196:197] op_sel_hi:[1,0]
	v_pk_mul_f32 v[188:189], v[140:141], v[196:197] op_sel_hi:[1,0]
	v_pk_mul_f32 v[190:191], v[142:143], v[196:197] op_sel_hi:[1,0]
	v_pk_mul_f32 v[184:185], v[26:27], v[184:185]
	v_pk_mul_f32 v[186:187], v[28:29], v[186:187]
	v_pk_mul_f32 v[188:189], v[30:31], v[188:189]
	v_pk_mul_f32 v[190:191], v[32:33], v[190:191]
	v_cvt_pk_bf16_f32 v136, v184, v185
	v_cvt_pk_bf16_f32 v137, v186, v187
	v_cvt_pk_bf16_f32 v138, v188, v189
	v_cvt_pk_bf16_f32 v139, v190, v191
	s_add_i32 s10, s24, 0x0
	s_lshl_b32 s11, s10, 11
	s_add_u32 s4, s26, s11
	s_addc_u32 s5, s27, 0
	global_store_dwordx4 v0, v[136:139], s[4:5] offset:1024
	v_pk_mul_f32 v[184:185], v[144:145], v[198:199] op_sel_hi:[1,0]
	v_pk_mul_f32 v[186:187], v[146:147], v[198:199] op_sel_hi:[1,0]
	v_pk_mul_f32 v[188:189], v[148:149], v[198:199] op_sel_hi:[1,0]
	v_pk_mul_f32 v[190:191], v[150:151], v[198:199] op_sel_hi:[1,0]
	v_pk_mul_f32 v[184:185], v[26:27], v[184:185]
	v_pk_mul_f32 v[186:187], v[28:29], v[186:187]
	v_pk_mul_f32 v[188:189], v[30:31], v[188:189]
	v_pk_mul_f32 v[190:191], v[32:33], v[190:191]
	v_cvt_pk_bf16_f32 v144, v184, v185
	v_cvt_pk_bf16_f32 v145, v186, v187
	v_cvt_pk_bf16_f32 v146, v188, v189
	v_cvt_pk_bf16_f32 v147, v190, v191
	s_add_i32 s10, s24, 0x600
	s_lshl_b32 s11, s10, 11
	s_add_u32 s4, s26, s11
	s_addc_u32 s5, s27, 0
	global_store_dwordx4 v0, v[144:147], s[4:5] offset:1024
	v_pk_mul_f32 v[184:185], v[152:153], v[200:201] op_sel_hi:[1,0]
	v_pk_mul_f32 v[186:187], v[154:155], v[200:201] op_sel_hi:[1,0]
	v_pk_mul_f32 v[188:189], v[156:157], v[200:201] op_sel_hi:[1,0]
	v_pk_mul_f32 v[190:191], v[158:159], v[200:201] op_sel_hi:[1,0]
	v_pk_mul_f32 v[184:185], v[26:27], v[184:185]
	v_pk_mul_f32 v[186:187], v[28:29], v[186:187]
	v_pk_mul_f32 v[188:189], v[30:31], v[188:189]
	v_pk_mul_f32 v[190:191], v[32:33], v[190:191]
	v_cvt_pk_bf16_f32 v152, v184, v185
	v_cvt_pk_bf16_f32 v153, v186, v187
	v_cvt_pk_bf16_f32 v154, v188, v189
	v_cvt_pk_bf16_f32 v155, v190, v191
	s_add_i32 s10, s24, 0xc00
	s_lshl_b32 s11, s10, 11
	s_add_u32 s4, s26, s11
	s_addc_u32 s5, s27, 0
	global_store_dwordx4 v0, v[152:155], s[4:5] offset:1024
	v_pk_mul_f32 v[184:185], v[160:161], v[202:203] op_sel_hi:[1,0]
	v_pk_mul_f32 v[186:187], v[162:163], v[202:203] op_sel_hi:[1,0]
	v_pk_mul_f32 v[188:189], v[164:165], v[202:203] op_sel_hi:[1,0]
	v_pk_mul_f32 v[190:191], v[166:167], v[202:203] op_sel_hi:[1,0]
	v_pk_mul_f32 v[184:185], v[26:27], v[184:185]
	v_pk_mul_f32 v[186:187], v[28:29], v[186:187]
	v_pk_mul_f32 v[188:189], v[30:31], v[188:189]
	v_pk_mul_f32 v[190:191], v[32:33], v[190:191]
	v_cvt_pk_bf16_f32 v160, v184, v185
	v_cvt_pk_bf16_f32 v161, v186, v187
	v_cvt_pk_bf16_f32 v162, v188, v189
	v_cvt_pk_bf16_f32 v163, v190, v191
	s_add_i32 s10, s24, 0x1200
	s_lshl_b32 s11, s10, 11
	s_add_u32 s4, s26, s11
	s_addc_u32 s5, s27, 0
	global_store_dwordx4 v0, v[160:163], s[4:5] offset:1024
	v_pk_mul_f32 v[184:185], v[168:169], v[204:205] op_sel_hi:[1,0]
	v_pk_mul_f32 v[186:187], v[170:171], v[204:205] op_sel_hi:[1,0]
	v_pk_mul_f32 v[188:189], v[172:173], v[204:205] op_sel_hi:[1,0]
	v_pk_mul_f32 v[190:191], v[174:175], v[204:205] op_sel_hi:[1,0]
	v_pk_mul_f32 v[184:185], v[26:27], v[184:185]
	v_pk_mul_f32 v[186:187], v[28:29], v[186:187]
	v_pk_mul_f32 v[188:189], v[30:31], v[188:189]
	v_pk_mul_f32 v[190:191], v[32:33], v[190:191]
	v_cvt_pk_bf16_f32 v168, v184, v185
	v_cvt_pk_bf16_f32 v169, v186, v187
	v_cvt_pk_bf16_f32 v170, v188, v189
	v_cvt_pk_bf16_f32 v171, v190, v191
	s_add_i32 s10, s24, 0x1800
	s_lshl_b32 s11, s10, 11
	s_add_u32 s4, s26, s11
	s_addc_u32 s5, s27, 0
	global_store_dwordx4 v0, v[168:171], s[4:5] offset:1024
	v_pk_mul_f32 v[184:185], v[176:177], v[206:207] op_sel_hi:[1,0]
	v_pk_mul_f32 v[186:187], v[178:179], v[206:207] op_sel_hi:[1,0]
	v_pk_mul_f32 v[188:189], v[180:181], v[206:207] op_sel_hi:[1,0]
	v_pk_mul_f32 v[190:191], v[182:183], v[206:207] op_sel_hi:[1,0]
	v_pk_mul_f32 v[184:185], v[26:27], v[184:185]
	v_pk_mul_f32 v[186:187], v[28:29], v[186:187]
	v_pk_mul_f32 v[188:189], v[30:31], v[188:189]
	v_pk_mul_f32 v[190:191], v[32:33], v[190:191]
	v_cvt_pk_bf16_f32 v176, v184, v185
	v_cvt_pk_bf16_f32 v177, v186, v187
	v_cvt_pk_bf16_f32 v178, v188, v189
	v_cvt_pk_bf16_f32 v179, v190, v191
	s_add_i32 s10, s24, 0x1e00
	s_lshl_b32 s11, s10, 11
	s_add_u32 s4, s26, s11
	s_addc_u32 s5, s27, 0
	global_store_dwordx4 v0, v[176:179], s[4:5] offset:1024
	s_waitcnt vmcnt(22)
	s_add_i32 s10, s24, 0x2400
	s_and_b32 s11, s10, 0xfff
	s_cmp_lg_u32 s11, 0
	s_cbranch_scc1 .Lc5_k1_6
	v_mov_b32_e32 v48, 0
	v_mov_b32_e32 v49, 0
	v_mov_b32_e32 v50, 0
	v_mov_b32_e32 v51, 0

; template <int NR>
; __device__ __forceinline__ void conv_rows(const Args& a, int r0, int rstride, int lane) {
;     ...
;     for (int i = 0; i < NR; ++i) { const int row = r0 + i * rstride, t = row & (SEQ - 1);
;         bq[i] = *(const v4u*)(BCp + (size_t)row * 512 + c0); u0[i] = *(const v4u*)(CUp + (size_t)row * 512 + c0);
;         u1[i] = (v4u){0, 0, 0, 0}; u2[i] = (v4u){0, 0, 0, 0};
;         if (t >= 1) u1[i] = *(const v4u*)(CUp + (size_t)(row - 1) * 512 + c0);
;         if (t >= 2) u2[i] = *(const v4u*)(CUp + (size_t)(row - 2) * 512 + c0); }
;     const float* cw = a.in[I_CONVW] + c0; const float* gn = a.in[I_CONVN] + c0;
;     const f32x4 w0a = *(const f32x4*)(cw), w0b = *(const f32x4*)(cw + 4), w1a = *(const f32x4*)(cw + 512), w1b = *(const f32x4*)(cw + 516), w2a = *(const f32x4*)(cw + 1024), w2b = *(const f32x4*)(cw + 1028);
;     const f32x4 ga = *(const f32x4*)(gn), gb = *(const f32x4*)(gn + 4);
; #pragma unroll
;     for (int i = 0; i < NR; ++i) { const int row = r0 + i * rstride; float y[8]; float s = 0.f;
; #pragma unroll
;         for (int j = 0; j < 8; ++j) { const int sh = (j & 1) * 16; const unsigned ub = bq[i][j >> 1], x0 = u0[i][j >> 1], x1 = u1[i][j >> 1], x2 = u2[i][j >> 1];
;             const float B = __uint_as_float(((ub >> sh) & 0xffffu) << 16), c_0 = __uint_as_float(((x0 >> sh) & 0xffffu) << 16), c_1 = __uint_as_float(((x1 >> sh) & 0xffffu) << 16), c_2 = __uint_as_float(((x2 >> sh) & 0xffffu) << 16);
;             const float k0 = j < 4 ? w0a[j & 3] : w0b[j & 3], k1 = j < 4 ? w1a[j & 3] : w1b[j & 3], k2 = j < 4 ? w2a[j & 3] : w2b[j & 3];
;             y[j] = B * (k0 * c_2 + k1 * c_1 + k2 * c_0); s += y[j] * y[j]; }
.Lc5_k2_6:
	v_lshlrev_b32_e32 v184, 16, v52
	v_and_b32_e32 v185, 0xffff0000, v52
	v_lshlrev_b32_e32 v186, 16, v48
	v_and_b32_e32 v187, 0xffff0000, v48
	v_lshlrev_b32_e32 v188, 16, v44
	v_and_b32_e32 v189, 0xffff0000, v44
	v_lshlrev_b32_e32 v190, 16, v40
	v_and_b32_e32 v191, 0xffff0000, v40
	v_pk_mul_f32 v[192:193], v[2:3], v[184:185]
	v_pk_fma_f32 v[192:193], v[10:11], v[186:187], v[192:193]
	v_pk_fma_f32 v[192:193], v[18:19], v[188:189], v[192:193]
	v_pk_mul_f32 v[136:137], v[192:193], v[190:191]
	v_pk_mul_f32 v[194:195], v[136:137], v[136:137]
	v_lshlrev_b32_e32 v184, 16, v53
	v_and_b32_e32 v185, 0xffff0000, v53
	v_lshlrev_b32_e32 v186, 16, v49
	v_and_b32_e32 v187, 0xffff0000, v49
	v_lshlrev_b32_e32 v188, 16, v45
	v_and_b32_e32 v189, 0xffff0000, v45
	v_lshlrev_b32_e32 v190, 16, v41
	v_and_b32_e32 v191, 0xffff0000, v41
	v_pk_mul_f32 v[192:193], v[4:5], v[184:185]
	v_pk_fma_f32 v[192:193], v[12:13], v[186:187], v[192:193]
	v_pk_fma_f32 v[192:193], v[20:21], v[188:189], v[192:193]
	v_pk_mul_f32 v[138:139], v[192:193], v[190:191]
	v_pk_fma_f32 v[194:195], v[138:139], v[138:139], v[194:195]
	v_lshlrev_b32_e32 v184, 16, v54
	v_and_b32_e32 v185, 0xffff0000, v54
	v_lshlrev_b32_e32 v186, 16, v50
	v_and_b32_e32 v187, 0xffff0000, v50
	v_lshlrev_b32_e32 v188, 16, v46
	v_and_b32_e32 v189, 0xffff0000, v46
	v_lshlrev_b32_e32 v190, 16, v42
	v_and_b32_e32 v191, 0xffff0000, v42
	v_pk_mul_f32 v[192:193], v[6:7], v[184:185]
	v_pk_fma_f32 v[192:193], v[14:15], v[186:187], v[192:193]
	v_pk_fma_f32 v[192:193], v[22:23], v[188:189], v[192:193]
	v_pk_mul_f32 v[140:141], v[192:193], v[190:191]
	v_pk_fma_f32 v[194:195], v[140:141], v[140:141], v[194:195]
	v_lshlrev_b32_e32 v184, 16, v55
	v_and_b32_e32 v185, 0xffff0000, v55
	v_lshlrev_b32_e32 v186, 16, v51
	v_and_b32_e32 v187, 0xffff0000, v51
	v_lshlrev_b32_e32 v188, 16, v47
	v_and_b32_e32 v189, 0xffff0000, v47
	v_lshlrev_b32_e32 v190, 16, v43
	v_and_b32_e32 v191, 0xffff0000, v43
	v_pk_mul_f32 v[192:193], v[8:9], v[184:185]
	v_pk_fma_f32 v[192:193], v[16:17], v[186:187], v[192:193]
	v_pk_fma_f32 v[192:193], v[24:25], v[188:189], v[192:193]
	v_pk_mul_f32 v[142:143], v[192:193], v[190:191]
	v_pk_fma_f32 v[194:195], v[142:143], v[142:143], v[194:195]
	v_add_f32_e32 v196, v194, v195
	s_waitcnt vmcnt(18)
	s_add_i32 s10, s24, 0x2a00
	s_and_b32 s11, s10, 0xfff
	s_cmp_lg_u32 s11, 0
	s_cbranch_scc1 .Lc5_k1_7
	v_mov_b32_e32 v64, 0
	v_mov_b32_e32 v65, 0
	v_mov_b32_e32 v66, 0
	v_mov_b32_e32 v67, 0

; template <int NR>
; __device__ __forceinline__ void conv_rows(const Args& a, int r0, int rstride, int lane) {
;     ...
;     for (int i = 0; i < NR; ++i) { const int row = r0 + i * rstride, t = row & (SEQ - 1);
;         bq[i] = *(const v4u*)(BCp + (size_t)row * 512 + c0); u0[i] = *(const v4u*)(CUp + (size_t)row * 512 + c0);
;         u1[i] = (v4u){0, 0, 0, 0}; u2[i] = (v4u){0, 0, 0, 0};
;         if (t >= 1) u1[i] = *(const v4u*)(CUp + (size_t)(row - 1) * 512 + c0);
;         if (t >= 2) u2[i] = *(const v4u*)(CUp + (size_t)(row - 2) * 512 + c0); }
;     const float* cw = a.in[I_CONVW] + c0; const float* gn = a.in[I_CONVN] + c0;
;     const f32x4 w0a = *(const f32x4*)(cw), w0b = *(const f32x4*)(cw + 4), w1a = *(const f32x4*)(cw + 512), w1b = *(const f32x4*)(cw + 516), w2a = *(const f32x4*)(cw + 1024), w2b = *(const f32x4*)(cw + 1028);
;     const f32x4 ga = *(const f32x4*)(gn), gb = *(const f32x4*)(gn + 4);
; #pragma unroll
;     for (int i = 0; i < NR; ++i) { const int row = r0 + i * rstride; float y[8]; float s = 0.f;
; #pragma unroll
;         for (int j = 0; j < 8; ++j) { const int sh = (j & 1) * 16; const unsigned ub = bq[i][j >> 1], x0 = u0[i][j >> 1], x1 = u1[i][j >> 1], x2 = u2[i][j >> 1];
;             const float B = __uint_as_float(((ub >> sh) & 0xffffu) << 16), c_0 = __uint_as_float(((x0 >> sh) & 0xffffu) << 16), c_1 = __uint_as_float(((x1 >> sh) & 0xffffu) << 16), c_2 = __uint_as_float(((x2 >> sh) & 0xffffu) << 16);
;             const float k0 = j < 4 ? w0a[j & 3] : w0b[j & 3], k1 = j < 4 ? w1a[j & 3] : w1b[j & 3], k2 = j < 4 ? w2a[j & 3] : w2b[j & 3];
;             y[j] = B * (k0 * c_2 + k1 * c_1 + k2 * c_0); s += y[j] * y[j]; }
.Lc5_k2_7:
	v_lshlrev_b32_e32 v184, 16, v68
	v_and_b32_e32 v185, 0xffff0000, v68
	v_lshlrev_b32_e32 v186, 16, v64
	v_and_b32_e32 v187, 0xffff0000, v64
	v_lshlrev_b32_e32 v188, 16, v60
	v_and_b32_e32 v189, 0xffff0000, v60
	v_lshlrev_b32_e32 v190, 16, v56
	v_and_b32_e32 v191, 0xffff0000, v56
	v_pk_mul_f32 v[192:193], v[2:3], v[184:185]
	v_pk_fma_f32 v[192:193], v[10:11], v[186:187], v[192:193]
	v_pk_fma_f32 v[192:193], v[18:19], v[188:189], v[192:193]
	v_pk_mul_f32 v[144:145], v[192:193], v[190:191]
	v_pk_mul_f32 v[194:195], v[144:145], v[144:145]
	v_lshlrev_b32_e32 v184, 16, v69
	v_and_b32_e32 v185, 0xffff0000, v69
	v_lshlrev_b32_e32 v186, 16, v65
	v_and_b32_e32 v187, 0xffff0000, v65
	v_lshlrev_b32_e32 v188, 16, v61
	v_and_b32_e32 v189, 0xffff0000, v61
	v_lshlrev_b32_e32 v190, 16, v57
	v_and_b32_e32 v191, 0xffff0000, v57
	v_pk_mul_f32 v[192:193], v[4:5], v[184:185]
	v_pk_fma_f32 v[192:193], v[12:13], v[186:187], v[192:193]
	v_pk_fma_f32 v[192:193], v[20:21], v[188:189], v[192:193]
	v_pk_mul_f32 v[146:147], v[192:193], v[190:191]
	v_pk_fma_f32 v[194:195], v[146:147], v[146:147], v[194:195]
	v_lshlrev_b32_e32 v184, 16, v70
	v_and_b32_e32 v185, 0xffff0000, v70
	v_lshlrev_b32_e32 v186, 16, v66
	v_and_b32_e32 v187, 0xffff0000, v66
	v_lshlrev_b32_e32 v188, 16, v62
	v_and_b32_e32 v189, 0xffff0000, v62
	v_lshlrev_b32_e32 v190, 16, v58
	v_and_b32_e32 v191, 0xffff0000, v58
	v_pk_mul_f32 v[192:193], v[6:7], v[184:185]
	v_pk_fma_f32 v[192:193], v[14:15], v[186:187], v[192:193]
	v_pk_fma_f32 v[192:193], v[22:23], v[188:189], v[192:193]
	v_pk_mul_f32 v[148:149], v[192:193], v[190:191]
	v_pk_fma_f32 v[194:195], v[148:149], v[148:149], v[194:195]
	v_lshlrev_b32_e32 v184, 16, v71
	v_and_b32_e32 v185, 0xffff0000, v71
	v_lshlrev_b32_e32 v186, 16, v67
	v_and_b32_e32 v187, 0xffff0000, v67
	v_lshlrev_b32_e32 v188, 16, v63
	v_and_b32_e32 v189, 0xffff0000, v63
	v_lshlrev_b32_e32 v190, 16, v59
	v_and_b32_e32 v191, 0xffff0000, v59
	v_pk_mul_f32 v[192:193], v[8:9], v[184:185]
	v_pk_fma_f32 v[192:193], v[16:17], v[186:187], v[192:193]
	v_pk_fma_f32 v[192:193], v[24:25], v[188:189], v[192:193]
	v_pk_mul_f32 v[150:151], v[192:193], v[190:191]
	v_pk_fma_f32 v[194:195], v[150:151], v[150:151], v[194:195]
	v_add_f32_e32 v198, v194, v195
	s_waitcnt vmcnt(14)
	s_add_i32 s10, s24, 0x3000
	s_and_b32 s11, s10, 0xfff
	s_cmp_lg_u32 s11, 0
	s_cbranch_scc1 .Lc5_k1_8
	v_mov_b32_e32 v80, 0
	v_mov_b32_e32 v81, 0
	v_mov_b32_e32 v82, 0
	v_mov_b32_e32 v83, 0

; template <int NR>
; __device__ __forceinline__ void conv_rows(const Args& a, int r0, int rstride, int lane) {
;     ...
;     for (int i = 0; i < NR; ++i) { const int row = r0 + i * rstride, t = row & (SEQ - 1);
;         bq[i] = *(const v4u*)(BCp + (size_t)row * 512 + c0); u0[i] = *(const v4u*)(CUp + (size_t)row * 512 + c0);
;         u1[i] = (v4u){0, 0, 0, 0}; u2[i] = (v4u){0, 0, 0, 0};
;         if (t >= 1) u1[i] = *(const v4u*)(CUp + (size_t)(row - 1) * 512 + c0);
;         if (t >= 2) u2[i] = *(const v4u*)(CUp + (size_t)(row - 2) * 512 + c0); }
;     const float* cw = a.in[I_CONVW] + c0; const float* gn = a.in[I_CONVN] + c0;
;     const f32x4 w0a = *(const f32x4*)(cw), w0b = *(const f32x4*)(cw + 4), w1a = *(const f32x4*)(cw + 512), w1b = *(const f32x4*)(cw + 516), w2a = *(const f32x4*)(cw + 1024), w2b = *(const f32x4*)(cw + 1028);
;     const f32x4 ga = *(const f32x4*)(gn), gb = *(const f32x4*)(gn + 4);
; #pragma unroll
;     for (int i = 0; i < NR; ++i) { const int row = r0 + i * rstride; float y[8]; float s = 0.f;
; #pragma unroll
;         for (int j = 0; j < 8; ++j) { const int sh = (j & 1) * 16; const unsigned ub = bq[i][j >> 1], x0 = u0[i][j >> 1], x1 = u1[i][j >> 1], x2 = u2[i][j >> 1];
;             const float B = __uint_as_float(((ub >> sh) & 0xffffu) << 16), c_0 = __uint_as_float(((x0 >> sh) & 0xffffu) << 16), c_1 = __uint_as_float(((x1 >> sh) & 0xffffu) << 16), c_2 = __uint_as_float(((x2 >> sh) & 0xffffu) << 16);
;             const float k0 = j < 4 ? w0a[j & 3] : w0b[j & 3], k1 = j < 4 ? w1a[j & 3] : w1b[j & 3], k2 = j < 4 ? w2a[j & 3] : w2b[j & 3];
;             y[j] = B * (k0 * c_2 + k1 * c_1 + k2 * c_0); s += y[j] * y[j]; }
.Lc5_k2_8:
	v_lshlrev_b32_e32 v184, 16, v84
	v_and_b32_e32 v185, 0xffff0000, v84
	v_lshlrev_b32_e32 v186, 16, v80
	v_and_b32_e32 v187, 0xffff0000, v80
	v_lshlrev_b32_e32 v188, 16, v76
	v_and_b32_e32 v189, 0xffff0000, v76
	v_lshlrev_b32_e32 v190, 16, v72
	v_and_b32_e32 v191, 0xffff0000, v72
	v_pk_mul_f32 v[192:193], v[2:3], v[184:185]
	v_pk_fma_f32 v[192:193], v[10:11], v[186:187], v[192:193]
	v_pk_fma_f32 v[192:193], v[18:19], v[188:189], v[192:193]
	v_pk_mul_f32 v[152:153], v[192:193], v[190:191]
	v_pk_mul_f32 v[194:195], v[152:153], v[152:153]
	v_lshlrev_b32_e32 v184, 16, v85
	v_and_b32_e32 v185, 0xffff0000, v85
	v_lshlrev_b32_e32 v186, 16, v81
	v_and_b32_e32 v187, 0xffff0000, v81
	v_lshlrev_b32_e32 v188, 16, v77
	v_and_b32_e32 v189, 0xffff0000, v77
	v_lshlrev_b32_e32 v190, 16, v73
	v_and_b32_e32 v191, 0xffff0000, v73
	v_pk_mul_f32 v[192:193], v[4:5], v[184:185]
	v_pk_fma_f32 v[192:193], v[12:13], v[186:187], v[192:193]
	v_pk_fma_f32 v[192:193], v[20:21], v[188:189], v[192:193]
	v_pk_mul_f32 v[154:155], v[192:193], v[190:191]
	v_pk_fma_f32 v[194:195], v[154:155], v[154:155], v[194:195]
	v_lshlrev_b32_e32 v184, 16, v86
	v_and_b32_e32 v185, 0xffff0000, v86
	v_lshlrev_b32_e32 v186, 16, v82
	v_and_b32_e32 v187, 0xffff0000, v82
	v_lshlrev_b32_e32 v188, 16, v78
	v_and_b32_e32 v189, 0xffff0000, v78
	v_lshlrev_b32_e32 v190, 16, v74
	v_and_b32_e32 v191, 0xffff0000, v74
	v_pk_mul_f32 v[192:193], v[6:7], v[184:185]
	v_pk_fma_f32 v[192:193], v[14:15], v[186:187], v[192:193]
	v_pk_fma_f32 v[192:193], v[22:23], v[188:189], v[192:193]
	v_pk_mul_f32 v[156:157], v[192:193], v[190:191]
	v_pk_fma_f32 v[194:195], v[156:157], v[156:157], v[194:195]
	v_lshlrev_b32_e32 v184, 16, v87
	v_and_b32_e32 v185, 0xffff0000, v87
	v_lshlrev_b32_e32 v186, 16, v83
	v_and_b32_e32 v187, 0xffff0000, v83
	v_lshlrev_b32_e32 v188, 16, v79
	v_and_b32_e32 v189, 0xffff0000, v79
	v_lshlrev_b32_e32 v190, 16, v75
	v_and_b32_e32 v191, 0xffff0000, v75
	v_pk_mul_f32 v[192:193], v[8:9], v[184:185]
	v_pk_fma_f32 v[192:193], v[16:17], v[186:187], v[192:193]
	v_pk_fma_f32 v[192:193], v[24:25], v[188:189], v[192:193]
	v_pk_mul_f32 v[158:159], v[192:193], v[190:191]
	v_pk_fma_f32 v[194:195], v[158:159], v[158:159], v[194:195]
	v_add_f32_e32 v200, v194, v195
	s_waitcnt vmcnt(10)
	s_add_i32 s10, s24, 0x3600
	s_and_b32 s11, s10, 0xfff
	s_cmp_lg_u32 s11, 0
	s_cbranch_scc1 .Lc5_k1_9
	v_mov_b32_e32 v96, 0
	v_mov_b32_e32 v97, 0
	v_mov_b32_e32 v98, 0
	v_mov_b32_e32 v99, 0

; template <int NR>
; __device__ __forceinline__ void conv_rows(const Args& a, int r0, int rstride, int lane) {
;     ...
;     for (int i = 0; i < NR; ++i) { const int row = r0 + i * rstride, t = row & (SEQ - 1);
;         bq[i] = *(const v4u*)(BCp + (size_t)row * 512 + c0); u0[i] = *(const v4u*)(CUp + (size_t)row * 512 + c0);
;         u1[i] = (v4u){0, 0, 0, 0}; u2[i] = (v4u){0, 0, 0, 0};
;         if (t >= 1) u1[i] = *(const v4u*)(CUp + (size_t)(row - 1) * 512 + c0);
;         if (t >= 2) u2[i] = *(const v4u*)(CUp + (size_t)(row - 2) * 512 + c0); }
;     const float* cw = a.in[I_CONVW] + c0; const float* gn = a.in[I_CONVN] + c0;
;     const f32x4 w0a = *(const f32x4*)(cw), w0b = *(const f32x4*)(cw + 4), w1a = *(const f32x4*)(cw + 512), w1b = *(const f32x4*)(cw + 516), w2a = *(const f32x4*)(cw + 1024), w2b = *(const f32x4*)(cw + 1028);
;     const f32x4 ga = *(const f32x4*)(gn), gb = *(const f32x4*)(gn + 4);
; #pragma unroll
;     for (int i = 0; i < NR; ++i) { const int row = r0 + i * rstride; float y[8]; float s = 0.f;
; #pragma unroll
;         for (int j = 0; j < 8; ++j) { const int sh = (j & 1) * 16; const unsigned ub = bq[i][j >> 1], x0 = u0[i][j >> 1], x1 = u1[i][j >> 1], x2 = u2[i][j >> 1];
;             const float B = __uint_as_float(((ub >> sh) & 0xffffu) << 16), c_0 = __uint_as_float(((x0 >> sh) & 0xffffu) << 16), c_1 = __uint_as_float(((x1 >> sh) & 0xffffu) << 16), c_2 = __uint_as_float(((x2 >> sh) & 0xffffu) << 16);
;             const float k0 = j < 4 ? w0a[j & 3] : w0b[j & 3], k1 = j < 4 ? w1a[j & 3] : w1b[j & 3], k2 = j < 4 ? w2a[j & 3] : w2b[j & 3];
;             y[j] = B * (k0 * c_2 + k1 * c_1 + k2 * c_0); s += y[j] * y[j]; }
.Lc5_k2_9:
	v_lshlrev_b32_e32 v184, 16, v100
	v_and_b32_e32 v185, 0xffff0000, v100
	v_lshlrev_b32_e32 v186, 16, v96
	v_and_b32_e32 v187, 0xffff0000, v96
	v_lshlrev_b32_e32 v188, 16, v92
	v_and_b32_e32 v189, 0xffff0000, v92
	v_lshlrev_b32_e32 v190, 16, v88
	v_and_b32_e32 v191, 0xffff0000, v88
	v_pk_mul_f32 v[192:193], v[2:3], v[184:185]
	v_pk_fma_f32 v[192:193], v[10:11], v[186:187], v[192:193]
	v_pk_fma_f32 v[192:193], v[18:19], v[188:189], v[192:193]
	v_pk_mul_f32 v[160:161], v[192:193], v[190:191]
	v_pk_mul_f32 v[194:195], v[160:161], v[160:161]
	v_lshlrev_b32_e32 v184, 16, v101
	v_and_b32_e32 v185, 0xffff0000, v101
	v_lshlrev_b32_e32 v186, 16, v97
	v_and_b32_e32 v187, 0xffff0000, v97
	v_lshlrev_b32_e32 v188, 16, v93
	v_and_b32_e32 v189, 0xffff0000, v93
	v_lshlrev_b32_e32 v190, 16, v89
	v_and_b32_e32 v191, 0xffff0000, v89
	v_pk_mul_f32 v[192:193], v[4:5], v[184:185]
	v_pk_fma_f32 v[192:193], v[12:13], v[186:187], v[192:193]
	v_pk_fma_f32 v[192:193], v[20:21], v[188:189], v[192:193]
	v_pk_mul_f32 v[162:163], v[192:193], v[190:191]
	v_pk_fma_f32 v[194:195], v[162:163], v[162:163], v[194:195]
	v_lshlrev_b32_e32 v184, 16, v102
	v_and_b32_e32 v185, 0xffff0000, v102
	v_lshlrev_b32_e32 v186, 16, v98
	v_and_b32_e32 v187, 0xffff0000, v98
	v_lshlrev_b32_e32 v188, 16, v94
	v_and_b32_e32 v189, 0xffff0000, v94
	v_lshlrev_b32_e32 v190, 16, v90
	v_and_b32_e32 v191, 0xffff0000, v90
	v_pk_mul_f32 v[192:193], v[6:7], v[184:185]
	v_pk_fma_f32 v[192:193], v[14:15], v[186:187], v[192:193]
	v_pk_fma_f32 v[192:193], v[22:23], v[188:189], v[192:193]
	v_pk_mul_f32 v[164:165], v[192:193], v[190:191]
	v_pk_fma_f32 v[194:195], v[164:165], v[164:165], v[194:195]
	v_lshlrev_b32_e32 v184, 16, v103
	v_and_b32_e32 v185, 0xffff0000, v103
	v_lshlrev_b32_e32 v186, 16, v99
	v_and_b32_e32 v187, 0xffff0000, v99
	v_lshlrev_b32_e32 v188, 16, v95
	v_and_b32_e32 v189, 0xffff0000, v95
	v_lshlrev_b32_e32 v190, 16, v91
	v_and_b32_e32 v191, 0xffff0000, v91
	v_pk_mul_f32 v[192:193], v[8:9], v[184:185]
	v_pk_fma_f32 v[192:193], v[16:17], v[186:187], v[192:193]
	v_pk_fma_f32 v[192:193], v[24:25], v[188:189], v[192:193]
	v_pk_mul_f32 v[166:167], v[192:193], v[190:191]
	v_pk_fma_f32 v[194:195], v[166:167], v[166:167], v[194:195]
	v_add_f32_e32 v202, v194, v195
	s_waitcnt vmcnt(6)
	s_add_i32 s10, s24, 0x3c00
	s_cmpk_lt_u32 s24, 0x400
	s_cselect_b32 s10, s10, s24
	s_and_b32 s11, s10, 0xfff
	s_cmp_lg_u32 s11, 0
	s_cbranch_scc1 .Lc5_k1_10
	v_mov_b32_e32 v112, 0
	v_mov_b32_e32 v113, 0
	v_mov_b32_e32 v114, 0
	v_mov_b32_e32 v115, 0

; template <int NR>
; __device__ __forceinline__ void conv_rows(const Args& a, int r0, int rstride, int lane) {
;     ...
;     for (int i = 0; i < NR; ++i) { const int row = r0 + i * rstride; float y[8]; float s = 0.f;
; #pragma unroll
;         for (int j = 0; j < 8; ++j) { const int sh = (j & 1) * 16; const unsigned ub = bq[i][j >> 1], x0 = u0[i][j >> 1], x1 = u1[i][j >> 1], x2 = u2[i][j >> 1];
;             const float B = __uint_as_float(((ub >> sh) & 0xffffu) << 16), c_0 = __uint_as_float(((x0 >> sh) & 0xffffu) << 16), c_1 = __uint_as_float(((x1 >> sh) & 0xffffu) << 16), c_2 = __uint_as_float(((x2 >> sh) & 0xffffu) << 16);
;             const float k0 = j < 4 ? w0a[j & 3] : w0b[j & 3], k1 = j < 4 ? w1a[j & 3] : w1b[j & 3], k2 = j < 4 ? w2a[j & 3] : w2b[j & 3];
;             y[j] = B * (k0 * c_2 + k1 * c_1 + k2 * c_0); s += y[j] * y[j]; }
;         s = wave_sum(s); const float rs = rsqrtf(s * (1.f / 512.f) + EPS);
.Lc5_k2_10:
	v_lshlrev_b32_e32 v184, 16, v116
	v_and_b32_e32 v185, 0xffff0000, v116
	v_lshlrev_b32_e32 v186, 16, v112
	v_and_b32_e32 v187, 0xffff0000, v112
	v_lshlrev_b32_e32 v188, 16, v108
	v_and_b32_e32 v189, 0xffff0000, v108
	v_lshlrev_b32_e32 v190, 16, v104
	v_and_b32_e32 v191, 0xffff0000, v104
	v_pk_mul_f32 v[192:193], v[2:3], v[184:185]
	v_pk_fma_f32 v[192:193], v[10:11], v[186:187], v[192:193]
	v_pk_fma_f32 v[192:193], v[18:19], v[188:189], v[192:193]
	v_pk_mul_f32 v[168:169], v[192:193], v[190:191]
	v_pk_mul_f32 v[194:195], v[168:169], v[168:169]
	v_lshlrev_b32_e32 v184, 16, v117
	v_and_b32_e32 v185, 0xffff0000, v117
	v_lshlrev_b32_e32 v186, 16, v113
	v_and_b32_e32 v187, 0xffff0000, v113
	v_lshlrev_b32_e32 v188, 16, v109
	v_and_b32_e32 v189, 0xffff0000, v109
	v_lshlrev_b32_e32 v190, 16, v105
	v_and_b32_e32 v191, 0xffff0000, v105
	v_pk_mul_f32 v[192:193], v[4:5], v[184:185]
	v_pk_fma_f32 v[192:193], v[12:13], v[186:187], v[192:193]
	v_pk_fma_f32 v[192:193], v[20:21], v[188:189], v[192:193]
	v_pk_mul_f32 v[170:171], v[192:193], v[190:191]
	v_pk_fma_f32 v[194:195], v[170:171], v[170:171], v[194:195]
	v_lshlrev_b32_e32 v184, 16, v118
	v_and_b32_e32 v185, 0xffff0000, v118
	v_lshlrev_b32_e32 v186, 16, v114
	v_and_b32_e32 v187, 0xffff0000, v114
	v_lshlrev_b32_e32 v188, 16, v110
	v_and_b32_e32 v189, 0xffff0000, v110
	v_lshlrev_b32_e32 v190, 16, v106
	v_and_b32_e32 v191, 0xffff0000, v106
	v_pk_mul_f32 v[192:193], v[6:7], v[184:185]
	v_pk_fma_f32 v[192:193], v[14:15], v[186:187], v[192:193]
	v_pk_fma_f32 v[192:193], v[22:23], v[188:189], v[192:193]
	v_pk_mul_f32 v[172:173], v[192:193], v[190:191]
	v_pk_fma_f32 v[194:195], v[172:173], v[172:173], v[194:195]
	v_lshlrev_b32_e32 v184, 16, v119
	v_and_b32_e32 v185, 0xffff0000, v119
	v_lshlrev_b32_e32 v186, 16, v115
	v_and_b32_e32 v187, 0xffff0000, v115
	v_lshlrev_b32_e32 v188, 16, v111
	v_and_b32_e32 v189, 0xffff0000, v111
	v_lshlrev_b32_e32 v190, 16, v107
	v_and_b32_e32 v191, 0xffff0000, v107
	v_pk_mul_f32 v[192:193], v[8:9], v[184:185]
	v_pk_fma_f32 v[192:193], v[16:17], v[186:187], v[192:193]
	v_pk_fma_f32 v[192:193], v[24:25], v[188:189], v[192:193]
	v_pk_mul_f32 v[174:175], v[192:193], v[190:191]
	v_pk_fma_f32 v[194:195], v[174:175], v[174:175], v[194:195]
	v_add_f32_e32 v204, v194, v195
	v_xor_b32_e32 v210, 32, v208
	v_lshlrev_b32_e32 v210, 2, v210
	v_xor_b32_e32 v211, 16, v208
	v_lshlrev_b32_e32 v211, 2, v211
	v_xor_b32_e32 v212, 8, v208
	v_lshlrev_b32_e32 v212, 2, v212
	v_xor_b32_e32 v213, 4, v208
	v_lshlrev_b32_e32 v213, 2, v213
	v_xor_b32_e32 v214, 2, v208
	v_lshlrev_b32_e32 v214, 2, v214
	v_xor_b32_e32 v215, 1, v208
	v_lshlrev_b32_e32 v215, 2, v215
	v_mov_b32_e32 v216, 0x358637bd
	ds_bpermute_b32 v218, v210, v196
	ds_bpermute_b32 v220, v210, v198
	ds_bpermute_b32 v222, v210, v200
	ds_bpermute_b32 v224, v210, v202
	ds_bpermute_b32 v226, v210, v204
	s_waitcnt lgkmcnt(0)
	v_add_f32_e32 v196, v196, v218
	v_add_f32_e32 v198, v198, v220
	v_add_f32_e32 v200, v200, v222
	v_add_f32_e32 v202, v202, v224
	v_add_f32_e32 v204, v204, v226
	ds_bpermute_b32 v218, v211, v196
	ds_bpermute_b32 v220, v211, v198
	ds_bpermute_b32 v222, v211, v200
	ds_bpermute_b32 v224, v211, v202
	ds_bpermute_b32 v226, v211, v204
	s_waitcnt lgkmcnt(0)
	v_add_f32_e32 v196, v196, v218
	v_add_f32_e32 v198, v198, v220
	v_add_f32_e32 v200, v200, v222
	v_add_f32_e32 v202, v202, v224
	v_add_f32_e32 v204, v204, v226
	ds_bpermute_b32 v218, v212, v196
	ds_bpermute_b32 v220, v212, v198
	ds_bpermute_b32 v222, v212, v200
	ds_bpermute_b32 v224, v212, v202
	ds_bpermute_b32 v226, v212, v204
	s_waitcnt lgkmcnt(0)
	v_add_f32_e32 v196, v196, v218
	v_add_f32_e32 v198, v198, v220
	v_add_f32_e32 v200, v200, v222
	v_add_f32_e32 v202, v202, v224
	v_add_f32_e32 v204, v204, v226
	ds_bpermute_b32 v218, v213, v196
	ds_bpermute_b32 v220, v213, v198
	ds_bpermute_b32 v222, v213, v200
	ds_bpermute_b32 v224, v213, v202
	ds_bpermute_b32 v226, v213, v204
	s_waitcnt lgkmcnt(0)
	v_add_f32_e32 v196, v196, v218
	v_add_f32_e32 v198, v198, v220
	v_add_f32_e32 v200, v200, v222
	v_add_f32_e32 v202, v202, v224
	v_add_f32_e32 v204, v204, v226
	ds_bpermute_b32 v218, v214, v196
	ds_bpermute_b32 v220, v214, v198
	ds_bpermute_b32 v222, v214, v200
	ds_bpermute_b32 v224, v214, v202
	ds_bpermute_b32 v226, v214, v204
	s_waitcnt lgkmcnt(0)
	v_add_f32_e32 v196, v196, v218
	v_add_f32_e32 v198, v198, v220
	v_add_f32_e32 v200, v200, v222
	v_add_f32_e32 v202, v202, v224
	v_add_f32_e32 v204, v204, v226
	ds_bpermute_b32 v218, v215, v196
	ds_bpermute_b32 v220, v215, v198
	ds_bpermute_b32 v222, v215, v200
	ds_bpermute_b32 v224, v215, v202
	ds_bpermute_b32 v226, v215, v204
	s_waitcnt lgkmcnt(0)
; __device__ __forceinline__ unsigned pk2(float lo, float hi) { return pg8::cvt_pk_bf16(lo, hi); }
; template <int NR>
; __device__ __forceinline__ void conv_rows(const Args& a, int r0, int rstride, int lane) {
;     ...
;         s = wave_sum(s); const float rs = rsqrtf(s * (1.f / 512.f) + EPS);
;         v4u o; o.x = pk2(y[0] * rs * ga[0], y[1] * rs * ga[1]); o.y = pk2(y[2] * rs * ga[2], y[3] * rs * ga[3]); o.z = pk2(y[4] * rs * gb[0], y[5] * rs * gb[1]); o.w = pk2(y[6] * rs * gb[2], y[7] * rs * gb[3]);
;         pg8::st_wt16((bf16*)(ws + WS_MIX) + (size_t)row * 1024 + 512 + c0, o); }
	v_add_f32_e32 v196, v196, v218
	v_add_f32_e32 v198, v198, v220
	v_add_f32_e32 v200, v200, v222
	v_add_f32_e32 v202, v202, v224
	v_add_f32_e32 v204, v204, v226
	v_fmamk_f32 v196, v196, 0x3b000000, v216
	v_fmamk_f32 v198, v198, 0x3b000000, v216
	v_fmamk_f32 v200, v200, 0x3b000000, v216
	v_fmamk_f32 v202, v202, 0x3b000000, v216
	v_fmamk_f32 v204, v204, 0x3b000000, v216
	v_rsq_f32_e32 v196, v196
	v_rsq_f32_e32 v198, v198
	v_rsq_f32_e32 v200, v200
	v_rsq_f32_e32 v202, v202
	v_rsq_f32_e32 v204, v204
	s_nop 1
	v_pk_mul_f32 v[184:185], v[136:137], v[196:197] op_sel_hi:[1,0]
	v_pk_mul_f32 v[186:187], v[138:139], v[196:197] op_sel_hi:[1,0]
	v_pk_mul_f32 v[188:189], v[140:141], v[196:197] op_sel_hi:[1,0]
	v_pk_mul_f32 v[190:191], v[142:143], v[196:197] op_sel_hi:[1,0]
	v_pk_mul_f32 v[184:185], v[26:27], v[184:185]
	v_pk_mul_f32 v[186:187], v[28:29], v[186:187]
	v_pk_mul_f32 v[188:189], v[30:31], v[188:189]
	v_pk_mul_f32 v[190:191], v[32:33], v[190:191]
	v_cvt_pk_bf16_f32 v136, v184, v185
	v_cvt_pk_bf16_f32 v137, v186, v187
	v_cvt_pk_bf16_f32 v138, v188, v189
	v_cvt_pk_bf16_f32 v139, v190, v191
	s_add_i32 s10, s24, 0x2400
	s_lshl_b32 s11, s10, 11
	s_add_u32 s4, s26, s11
	s_addc_u32 s5, s27, 0
	global_store_dwordx4 v0, v[136:139], s[4:5] offset:1024
	v_pk_mul_f32 v[184:185], v[144:145], v[198:199] op_sel_hi:[1,0]
	v_pk_mul_f32 v[186:187], v[146:147], v[198:199] op_sel_hi:[1,0]
	v_pk_mul_f32 v[188:189], v[148:149], v[198:199] op_sel_hi:[1,0]
	v_pk_mul_f32 v[190:191], v[150:151], v[198:199] op_sel_hi:[1,0]
	v_pk_mul_f32 v[184:185], v[26:27], v[184:185]
	v_pk_mul_f32 v[186:187], v[28:29], v[186:187]
	v_pk_mul_f32 v[188:189], v[30:31], v[188:189]
	v_pk_mul_f32 v[190:191], v[32:33], v[190:191]
	v_cvt_pk_bf16_f32 v144, v184, v185
	v_cvt_pk_bf16_f32 v145, v186, v187
	v_cvt_pk_bf16_f32 v146, v188, v189
	v_cvt_pk_bf16_f32 v147, v190, v191
	s_add_i32 s10, s24, 0x2a00
	s_lshl_b32 s11, s10, 11
	s_add_u32 s4, s26, s11
	s_addc_u32 s5, s27, 0
	global_store_dwordx4 v0, v[144:147], s[4:5] offset:1024
	v_pk_mul_f32 v[184:185], v[152:153], v[200:201] op_sel_hi:[1,0]
	v_pk_mul_f32 v[186:187], v[154:155], v[200:201] op_sel_hi:[1,0]
	v_pk_mul_f32 v[188:189], v[156:157], v[200:201] op_sel_hi:[1,0]
	v_pk_mul_f32 v[190:191], v[158:159], v[200:201] op_sel_hi:[1,0]
	v_pk_mul_f32 v[184:185], v[26:27], v[184:185]
	v_pk_mul_f32 v[186:187], v[28:29], v[186:187]
	v_pk_mul_f32 v[188:189], v[30:31], v[188:189]
	v_pk_mul_f32 v[190:191], v[32:33], v[190:191]
	v_cvt_pk_bf16_f32 v152, v184, v185
	v_cvt_pk_bf16_f32 v153, v186, v187
	v_cvt_pk_bf16_f32 v154, v188, v189
	v_cvt_pk_bf16_f32 v155, v190, v191
	s_add_i32 s10, s24, 0x3000
	s_lshl_b32 s11, s10, 11
	s_add_u32 s4, s26, s11
	s_addc_u32 s5, s27, 0
	global_store_dwordx4 v0, v[152:155], s[4:5] offset:1024
	v_pk_mul_f32 v[184:185], v[160:161], v[202:203] op_sel_hi:[1,0]
	v_pk_mul_f32 v[186:187], v[162:163], v[202:203] op_sel_hi:[1,0]
	v_pk_mul_f32 v[188:189], v[164:165], v[202:203] op_sel_hi:[1,0]
	v_pk_mul_f32 v[190:191], v[166:167], v[202:203] op_sel_hi:[1,0]
	v_pk_mul_f32 v[184:185], v[26:27], v[184:185]
	v_pk_mul_f32 v[186:187], v[28:29], v[186:187]
	v_pk_mul_f32 v[188:189], v[30:31], v[188:189]
	v_pk_mul_f32 v[190:191], v[32:33], v[190:191]
	v_cvt_pk_bf16_f32 v160, v184, v185
	v_cvt_pk_bf16_f32 v161, v186, v187
	v_cvt_pk_bf16_f32 v162, v188, v189
	v_cvt_pk_bf16_f32 v163, v190, v191
	s_add_i32 s10, s24, 0x3600
	s_lshl_b32 s11, s10, 11
	s_add_u32 s4, s26, s11
	s_addc_u32 s5, s27, 0
	global_store_dwordx4 v0, v[160:163], s[4:5] offset:1024
	v_pk_mul_f32 v[184:185], v[168:169], v[204:205] op_sel_hi:[1,0]
	v_pk_mul_f32 v[186:187], v[170:171], v[204:205] op_sel_hi:[1,0]
	v_pk_mul_f32 v[188:189], v[172:173], v[204:205] op_sel_hi:[1,0]
	v_pk_mul_f32 v[190:191], v[174:175], v[204:205] op_sel_hi:[1,0]
	v_pk_mul_f32 v[184:185], v[26:27], v[184:185]
	v_pk_mul_f32 v[186:187], v[28:29], v[186:187]
	v_pk_mul_f32 v[188:189], v[30:31], v[188:189]
	v_pk_mul_f32 v[190:191], v[32:33], v[190:191]
	v_cvt_pk_bf16_f32 v168, v184, v185
	v_cvt_pk_bf16_f32 v169, v186, v187
	v_cvt_pk_bf16_f32 v170, v188, v189
	v_cvt_pk_bf16_f32 v171, v190, v191
	s_cmpk_lt_u32 s24, 0x400
	s_cbranch_scc0 .Lc5_nostore
	s_add_i32 s10, s24, 0x3c00
	s_lshl_b32 s11, s10, 11
	s_add_u32 s4, s26, s11
	s_addc_u32 s5, s27, 0
	global_store_dwordx4 v0, v[168:171], s[4:5] offset:1024
